# FFN-up epilogue: hidden-activation (H) and side-buffer stores issued non-temporal (written once, read by other XCDs in the next phase)
# speedup vs baseline: 1.0071x; 1.0022x over previous
; DI unsigned pk2(float lo, float hi) { f32x2 v = {lo, hi}; bf16x2_t b = __builtin_convertvector(v, bf16x2_t); return __builtin_bit_cast(unsigned, b); }
; DI float dpp_ror1(float v) { return __int_as_float(__builtin_amdgcn_mov_dpp(__float_as_int(v), 0x121, 0xf, 0xf, false)); }
;     DI void operator()(const f32x4 (&acc)[2][2][4][2], const Unit& u, int wr, int wc, int fr, int fq) const {
;     ...
;                 for (int n = 0; n < 2; ++n) {
;                     const f32x4 g = acc[ai][1][m][n], v = acc[ai][0][m][n];
;                     f32x4 c1, c2;
; #pragma unroll
;                     for (int j = 0; j < 4; ++j) { c1[j] = dpp_ror1(g[j]); c2[j] = dpp_ror2(g[j]); }
;                     f32x4 p1 = c1, p2 = c2;
;                     if (m == 0 && smp) {
;                         const float* sp = st + ((size_t)(seg - 512) * 2) * FF + col + 4 * n; const f32x4 s0 = *(const f32x4*)sp, s1 = *(const f32x4*)(sp + FF);
; #pragma unroll
;                         for (int j = 0; j < 4; ++j) { p1[j] = (fr == 0) ? s1[j] : c1[j]; p2[j] = (fr == 0) ? s0[j] : ((fr == 1) ? s1[j] : c2[j]); }
;                     }
;                     if (m > 0) {
; #pragma unroll
;                         for (int j = 0; j < 4; ++j) { p1[j] = (fr == 0) ? q1[n][j] : c1[j]; p2[j] = (fr < 2) ? q2[n][j] : c2[j]; }
;                     }
;                     q1[n] = c1; q2[n] = c2;
;                     const f32x4 ww0 = n ? w0.b : w0.a, ww1 = n ? w1.b : w1.a, ww2 = n ? w2.b : w2.a, wb = n ? bb.b : bb.a;
;                     const f32x4 y = ww0 * p2 + ww1 * p1 + ww2 * g + wb;
; #pragma unroll
;                     for (int j = 0; j < 4; ++j) hh[n][j] = silu_f(y[j]) * v[j];
;                 }
;                 if (m == 0 && fr < 2 && !smp) {
;                     float* o = SG0 + ((size_t)seg * 2 + fr) * FF + col; *(f32x4*)o = acc[ai][1][m][0]; *(f32x4*)(o + 4) = acc[ai][1][m][1];
;                     float* o2 = SV0 + ((size_t)seg * 2 + fr) * FF + col; *(f32x4*)o2 = acc[ai][0][m][0]; *(f32x4*)(o2 + 4) = acc[ai][0][m][1];
;                 } else {
;                     u32x4 w; w.x = pk2(hh[0][0], hh[0][1]); w.y = pk2(hh[0][2], hh[0][3]); w.z = pk2(hh[1][0], hh[1][1]); w.w = pk2(hh[1][2], hh[1][3]);
;                     *(u32x4*)(H + (size_t)row * FF + col) = w;
;                 }
.LBB0_96:
	s_ashr_i32 s31, s30, 31
	s_lshl_b64 s[0:1], s[30:31], 1
	s_nor_b64 s[4:5], s[42:43], s[4:5]
	s_and_saveexec_b64 s[6:7], s[4:5]
	s_xor_b64 s[6:7], exec, s[6:7]
	s_cbranch_execz .LBB0_98
	v_lshl_add_u64 v[178:179], s[0:1], 0, v[202:203]
	v_mov_b64_e32 v[180:181], s[22:23]
	v_mad_u64_u32 v[180:181], s[10:11], v178, s90, v[180:181]
	v_mad_i32_i24 v181, v179, s90, v181
	v_lshl_add_u64 v[180:181], v[180:181], 0, v[212:213]
	global_store_dwordx4 v[180:181], v[158:161], off nt
	global_store_dwordx4 v[180:181], v[150:153], off offset:16 nt
	v_mov_b64_e32 v[180:181], s[94:95]
	v_mad_u64_u32 v[180:181], s[10:11], v178, s90, v[180:181]
	v_mad_i32_i24 v181, v179, s90, v181
	v_lshl_add_u64 v[178:179], v[180:181], 0, v[212:213]
	global_store_dwordx4 v[178:179], v[154:157], off nt
	global_store_dwordx4 v[178:179], v[146:149], off offset:16 nt
.LBB0_98:
	s_or_saveexec_b64 s[6:7], s[6:7]
	s_lshl_b32 s10, s30, 6
	v_or_b32_e32 v64, s10, v202
	s_xor_b64 exec, exec, s[6:7]
	s_cbranch_execz .LBB0_100
	s_waitcnt vmcnt(0)
	v_pk_mul_f32 v[178:179], v[98:99], v[178:179]
	v_pk_mul_f32 v[180:181], v[100:101], v[180:181]
	v_pk_fma_f32 v[178:179], v[102:103], v[182:183], v[178:179]
	v_pk_fma_f32 v[180:181], v[104:105], v[184:185], v[180:181]
	v_pk_fma_f32 v[158:159], v[158:159], v[94:95], v[178:179]
	v_pk_fma_f32 v[160:161], v[160:161], v[96:97], v[180:181]
	v_pk_add_f32 v[158:159], v[90:91], v[158:159]
	v_pk_add_f32 v[160:161], v[92:93], v[160:161]
	v_mul_f32_e32 v178, 0xbfb8aa3b, v158
	v_mul_f32_e32 v179, 0xbfb8aa3b, v159
	v_exp_f32_e32 v178, v178
	v_exp_f32_e32 v179, v179
	v_mul_f32_e32 v180, 0xbfb8aa3b, v160
	v_mul_f32_e32 v181, 0xbfb8aa3b, v161
	v_exp_f32_e32 v180, v180
	v_exp_f32_e32 v181, v181
	v_add_f32_e32 v178, 1.0, v178
	v_add_f32_e32 v179, 1.0, v179
	v_rcp_f32_e32 v178, v178
	v_rcp_f32_e32 v179, v179
	v_add_f32_e32 v180, 1.0, v180
	v_add_f32_e32 v181, 1.0, v181
	v_rcp_f32_e32 v180, v180
	v_rcp_f32_e32 v181, v181
	v_pk_mul_f32 v[158:159], v[158:159], v[178:179]
	v_pk_mul_f32 v[178:179], v[74:75], v[190:191]
	v_pk_mul_f32 v[154:155], v[154:155], v[158:159]
	v_pk_mul_f32 v[158:159], v[160:161], v[180:181]
	v_pk_mul_f32 v[160:161], v[76:77], v[192:193]
	v_pk_fma_f32 v[178:179], v[82:83], v[186:187], v[178:179]
	v_pk_fma_f32 v[160:161], v[84:85], v[188:189], v[160:161]
	v_pk_fma_f32 v[150:151], v[150:151], v[66:67], v[178:179]
	v_pk_fma_f32 v[152:153], v[152:153], v[68:69], v[160:161]
	v_pk_add_f32 v[150:151], v[70:71], v[150:151]
	v_pk_add_f32 v[152:153], v[72:73], v[152:153]
	v_mul_f32_e32 v179, 0xbfb8aa3b, v150
	v_mul_f32_e32 v160, 0xbfb8aa3b, v153
	v_exp_f32_e32 v160, v160
	v_mul_f32_e32 v161, 0xbfb8aa3b, v152
	v_exp_f32_e32 v178, v161
	v_exp_f32_e32 v180, v179
	v_add_f32_e32 v160, 1.0, v160
	v_rcp_f32_e32 v161, v160
	v_add_f32_e32 v160, 1.0, v178
	v_mul_f32_e32 v178, 0xbfb8aa3b, v151
	v_exp_f32_e32 v178, v178
	v_rcp_f32_e32 v160, v160
	s_movk_i32 s11, 0x1600
	v_pk_mul_f32 v[156:157], v[156:157], v[158:159]
	v_add_f32_e32 v178, 1.0, v178
	v_rcp_f32_e32 v179, v178
	v_add_f32_e32 v178, 1.0, v180
	v_rcp_f32_e32 v178, v178
	v_pk_mul_f32 v[152:153], v[152:153], v[160:161]
	s_nop 0
	v_pk_mul_f32 v[152:153], v[148:149], v[152:153]
	v_pk_mul_f32 v[148:149], v[150:151], v[178:179]
	v_mov_b64_e32 v[150:151], s[54:55]
	v_pk_mul_f32 v[148:149], v[146:147], v[148:149]
	v_mad_i64_i32 v[150:151], s[88:89], v64, s11, v[150:151]
	v_cvt_pk_bf16_f32 v146, v154, v155
	v_cvt_pk_bf16_f32 v147, v156, v157
	v_cvt_pk_bf16_f32 v148, v148, v149
	v_cvt_pk_bf16_f32 v149, v152, v153
	v_lshl_add_u64 v[150:151], v[210:211], 1, v[150:151]
	global_store_dwordx4 v[150:151], v[146:149], off nt
.LBB0_100:
	s_or_b64 exec, exec, s[6:7]
	v_mov_b32_dpp v155, v142 row_ror:2 row_mask:0xf bank_mask:0xf
	v_mov_b32_dpp v157, v143 row_ror:2 row_mask:0xf bank_mask:0xf
	v_mov_b32_dpp v154, v142 row_ror:1 row_mask:0xf bank_mask:0xf
	v_mov_b32_dpp v156, v143 row_ror:1 row_mask:0xf bank_mask:0xf
	v_cndmask_b32_e64 v146, v155, v166, s[40:41]
	v_cndmask_b32_e64 v147, v157, v167, s[40:41]
	v_mov_b32_dpp v159, v144 row_ror:2 row_mask:0xf bank_mask:0xf
	v_mov_b32_dpp v161, v145 row_ror:2 row_mask:0xf bank_mask:0xf
	v_cndmask_b32_e64 v150, v154, v162, s[36:37]
	v_cndmask_b32_e64 v151, v156, v163, s[36:37]
	s_waitcnt vmcnt(0)
; DI unsigned pk2(float lo, float hi) { f32x2 v = {lo, hi}; bf16x2_t b = __builtin_convertvector(v, bf16x2_t); return __builtin_bit_cast(unsigned, b); }
;     DI void operator()(const f32x4 (&acc)[2][2][4][2], const Unit& u, int wr, int wc, int fr, int fq) const {
;     ...
;             for (int m = 0; m < 4; ++m) {
;                 const int row = seg * 64 + m * 16 + fr;
;                 f32x4 hh[2];
; #pragma unroll
;                 for (int n = 0; n < 2; ++n) {
;                     const f32x4 g = acc[ai][1][m][n], v = acc[ai][0][m][n];
;                     f32x4 c1, c2;
; #pragma unroll
;                     for (int j = 0; j < 4; ++j) { c1[j] = dpp_ror1(g[j]); c2[j] = dpp_ror2(g[j]); }
;                     f32x4 p1 = c1, p2 = c2;
;                     if (m == 0 && smp) {
;                         const float* sp = st + ((size_t)(seg - 512) * 2) * FF + col + 4 * n; const f32x4 s0 = *(const f32x4*)sp, s1 = *(const f32x4*)(sp + FF);
; #pragma unroll
;                         for (int j = 0; j < 4; ++j) { p1[j] = (fr == 0) ? s1[j] : c1[j]; p2[j] = (fr == 0) ? s0[j] : ((fr == 1) ? s1[j] : c2[j]); }
;                     }
;                     if (m > 0) {
; #pragma unroll
;                         for (int j = 0; j < 4; ++j) { p1[j] = (fr == 0) ? q1[n][j] : c1[j]; p2[j] = (fr < 2) ? q2[n][j] : c2[j]; }
;                     }
;                     q1[n] = c1; q2[n] = c2;
;                     const f32x4 ww0 = n ? w0.b : w0.a, ww1 = n ? w1.b : w1.a, ww2 = n ? w2.b : w2.a, wb = n ? bb.b : bb.a;
;                     const f32x4 y = ww0 * p2 + ww1 * p1 + ww2 * g + wb;
; #pragma unroll
;                     for (int j = 0; j < 4; ++j) hh[n][j] = silu_f(y[j]) * v[j];
;                 }
;                 if (m == 0 && fr < 2 && !smp) {
;                     float* o = SG0 + ((size_t)seg * 2 + fr) * FF + col; *(f32x4*)o = acc[ai][1][m][0]; *(f32x4*)(o + 4) = acc[ai][1][m][1];
;                     float* o2 = SV0 + ((size_t)seg * 2 + fr) * FF + col; *(f32x4*)o2 = acc[ai][0][m][0]; *(f32x4*)(o2 + 4) = acc[ai][0][m][1];
;                 } else {
;                     u32x4 w; w.x = pk2(hh[0][0], hh[0][1]); w.y = pk2(hh[0][2], hh[0][3]); w.z = pk2(hh[1][0], hh[1][1]); w.w = pk2(hh[1][2], hh[1][3]);
;                     *(u32x4*)(H + (size_t)row * FF + col) = w;
	v_pk_mul_f32 v[146:147], v[102:103], v[146:147]
	v_mov_b32_dpp v158, v144 row_ror:1 row_mask:0xf bank_mask:0xf
	v_mov_b32_dpp v160, v145 row_ror:1 row_mask:0xf bank_mask:0xf
	v_cndmask_b32_e64 v148, v159, v168, s[40:41]
	v_cndmask_b32_e64 v149, v161, v169, s[40:41]
	v_pk_fma_f32 v[146:147], v[98:99], v[150:151], v[146:147]
	v_cndmask_b32_e64 v152, v158, v164, s[36:37]
	v_cndmask_b32_e64 v153, v160, v165, s[36:37]
	v_pk_mul_f32 v[148:149], v[104:105], v[148:149]
	v_pk_fma_f32 v[142:143], v[142:143], v[94:95], v[146:147]
	v_pk_fma_f32 v[148:149], v[100:101], v[152:153], v[148:149]
	v_pk_add_f32 v[142:143], v[90:91], v[142:143]
	v_pk_fma_f32 v[144:145], v[144:145], v[96:97], v[148:149]
	v_mul_f32_e32 v146, 0xbfb8aa3b, v142
	v_mul_f32_e32 v147, 0xbfb8aa3b, v143
	v_exp_f32_e32 v146, v146
	v_exp_f32_e32 v147, v147
	v_pk_add_f32 v[144:145], v[92:93], v[144:145]
	v_mov_b32_dpp v165, v136 row_ror:2 row_mask:0xf bank_mask:0xf
	v_mul_f32_e32 v148, 0xbfb8aa3b, v144
	v_mul_f32_e32 v149, 0xbfb8aa3b, v145
	v_exp_f32_e32 v148, v148
	v_exp_f32_e32 v149, v149
	v_add_f32_e32 v146, 1.0, v146
	v_add_f32_e32 v147, 1.0, v147
	v_rcp_f32_e32 v146, v146
	v_rcp_f32_e32 v147, v147
	v_add_f32_e32 v148, 1.0, v148
	v_add_f32_e32 v149, 1.0, v149
	v_rcp_f32_e32 v148, v148
	v_rcp_f32_e32 v149, v149
	v_mov_b32_dpp v167, v137 row_ror:2 row_mask:0xf bank_mask:0xf
	v_pk_mul_f32 v[142:143], v[142:143], v[146:147]
	v_mov_b32_dpp v164, v136 row_ror:1 row_mask:0xf bank_mask:0xf
	v_mov_b32_dpp v166, v137 row_ror:1 row_mask:0xf bank_mask:0xf
	v_cndmask_b32_e64 v146, v165, v176, s[40:41]
	v_cndmask_b32_e64 v147, v167, v177, s[40:41]
	v_mov_b32_dpp v153, v134 row_ror:2 row_mask:0xf bank_mask:0xf
	v_mov_b32_dpp v163, v135 row_ror:2 row_mask:0xf bank_mask:0xf
	v_pk_mul_f32 v[146:147], v[84:85], v[146:147]
	v_cndmask_b32_e64 v150, v164, v172, s[36:37]
	v_cndmask_b32_e64 v151, v166, v173, s[36:37]
	v_pk_mul_f32 v[138:139], v[138:139], v[142:143]
	v_pk_mul_f32 v[142:143], v[144:145], v[148:149]
	v_mov_b32_dpp v152, v134 row_ror:1 row_mask:0xf bank_mask:0xf
	v_mov_b32_dpp v162, v135 row_ror:1 row_mask:0xf bank_mask:0xf
	v_cndmask_b32_e64 v144, v153, v174, s[40:41]
	v_cndmask_b32_e64 v145, v163, v175, s[40:41]
	v_pk_fma_f32 v[146:147], v[76:77], v[150:151], v[146:147]
	v_pk_mul_f32 v[144:145], v[82:83], v[144:145]
	v_cndmask_b32_e64 v148, v152, v170, s[36:37]
	v_cndmask_b32_e64 v149, v162, v171, s[36:37]
	v_pk_fma_f32 v[136:137], v[136:137], v[68:69], v[146:147]
	v_pk_fma_f32 v[144:145], v[74:75], v[148:149], v[144:145]
	v_pk_add_f32 v[136:137], v[72:73], v[136:137]
	v_pk_fma_f32 v[134:135], v[134:135], v[66:67], v[144:145]
	v_mul_f32_e32 v144, 0xbfb8aa3b, v137
	v_exp_f32_e32 v144, v144
	v_mul_f32_e32 v145, 0xbfb8aa3b, v136
	v_exp_f32_e32 v146, v145
	v_pk_add_f32 v[134:135], v[70:71], v[134:135]
	v_add_f32_e32 v144, 1.0, v144
	v_rcp_f32_e32 v145, v144
	v_add_f32_e32 v144, 1.0, v146
	v_mul_f32_e32 v146, 0xbfb8aa3b, v135
	v_exp_f32_e32 v146, v146
	v_mul_f32_e32 v147, 0xbfb8aa3b, v134
	v_exp_f32_e32 v148, v147
	v_rcp_f32_e32 v144, v144
	v_add_f32_e32 v146, 1.0, v146
	v_rcp_f32_e32 v147, v146
	v_add_f32_e32 v146, 1.0, v148
	v_rcp_f32_e32 v146, v146
	v_pk_mul_f32 v[136:137], v[136:137], v[144:145]
	v_pk_mul_f32 v[140:141], v[140:141], v[142:143]
	v_pk_mul_f32 v[132:133], v[132:133], v[136:137]
	v_pk_mul_f32 v[134:135], v[134:135], v[146:147]
	v_mov_b32_dpp v149, v126 row_ror:2 row_mask:0xf bank_mask:0xf
	v_mov_b32_dpp v151, v127 row_ror:2 row_mask:0xf bank_mask:0xf
	v_pk_mul_f32 v[130:131], v[130:131], v[134:135]
	v_or_b32_e32 v142, 16, v64
	v_cvt_pk_bf16_f32 v135, v140, v141
	v_cvt_pk_bf16_f32 v137, v132, v133
	v_mov_b64_e32 v[132:133], s[54:55]
	v_mov_b32_dpp v148, v126 row_ror:1 row_mask:0xf bank_mask:0xf
	v_mov_b32_dpp v150, v127 row_ror:1 row_mask:0xf bank_mask:0xf
	v_mov_b32_dpp v169, v128 row_ror:2 row_mask:0xf bank_mask:0xf
	v_mov_b32_dpp v171, v129 row_ror:2 row_mask:0xf bank_mask:0xf
	v_cndmask_b32_e64 v140, v149, v155, s[40:41]
	v_cndmask_b32_e64 v141, v151, v157, s[40:41]
	v_cvt_pk_bf16_f32 v134, v138, v139
	v_mad_i64_i32 v[138:139], s[6:7], v142, s27, v[132:133]
	v_mov_b32_dpp v168, v128 row_ror:1 row_mask:0xf bank_mask:0xf
	v_mov_b32_dpp v170, v129 row_ror:1 row_mask:0xf bank_mask:0xf
	v_cndmask_b32_e64 v142, v169, v159, s[40:41]
	v_cndmask_b32_e64 v143, v171, v161, s[40:41]
	v_cndmask_b32_e64 v144, v148, v154, s[36:37]
	v_cndmask_b32_e64 v145, v150, v156, s[36:37]
	v_pk_mul_f32 v[140:141], v[102:103], v[140:141]
	v_cndmask_b32_e64 v146, v168, v158, s[36:37]
	v_cndmask_b32_e64 v147, v170, v160, s[36:37]
	v_pk_mul_f32 v[142:143], v[104:105], v[142:143]
	v_pk_fma_f32 v[140:141], v[98:99], v[144:145], v[140:141]
	v_pk_fma_f32 v[142:143], v[100:101], v[146:147], v[142:143]
	v_pk_fma_f32 v[126:127], v[126:127], v[94:95], v[140:141]
	v_pk_fma_f32 v[128:129], v[128:129], v[96:97], v[142:143]
	v_pk_add_f32 v[126:127], v[90:91], v[126:127]
	v_pk_add_f32 v[128:129], v[92:93], v[128:129]
	v_mul_f32_e32 v140, 0xbfb8aa3b, v126
	v_mul_f32_e32 v141, 0xbfb8aa3b, v127
	v_exp_f32_e32 v140, v140
	v_exp_f32_e32 v141, v141
	v_mul_f32_e32 v142, 0xbfb8aa3b, v128
	v_mul_f32_e32 v143, 0xbfb8aa3b, v129
	v_exp_f32_e32 v142, v142
	v_exp_f32_e32 v143, v143
	v_add_f32_e32 v140, 1.0, v140
	v_add_f32_e32 v141, 1.0, v141
	v_rcp_f32_e32 v140, v140
	v_rcp_f32_e32 v141, v141
	v_add_f32_e32 v142, 1.0, v142
	v_add_f32_e32 v143, 1.0, v143
	v_rcp_f32_e32 v142, v142
	v_rcp_f32_e32 v143, v143
	v_cvt_pk_bf16_f32 v136, v130, v131
	v_lshlrev_b64 v[130:131], 1, v[210:211]
	v_lshl_add_u64 v[138:139], v[138:139], 0, v[130:131]
	v_mov_b32_dpp v145, v120 row_ror:2 row_mask:0xf bank_mask:0xf
	v_mov_b32_dpp v147, v121 row_ror:2 row_mask:0xf bank_mask:0xf
; DI unsigned pk2(float lo, float hi) { f32x2 v = {lo, hi}; bf16x2_t b = __builtin_convertvector(v, bf16x2_t); return __builtin_bit_cast(unsigned, b); }
; DI float dpp_ror1(float v) { return __int_as_float(__builtin_amdgcn_mov_dpp(__float_as_int(v), 0x121, 0xf, 0xf, false)); }
; DI float dpp_ror2(float v) { return __int_as_float(__builtin_amdgcn_mov_dpp(__float_as_int(v), 0x122, 0xf, 0xf, false)); }
;     DI void operator()(const f32x4 (&acc)[2][2][4][2], const Unit& u, int wr, int wc, int fr, int fq) const {
;     ...
;                     const f32x4 g = acc[ai][1][m][n], v = acc[ai][0][m][n];
;                     f32x4 c1, c2;
; #pragma unroll
;                     for (int j = 0; j < 4; ++j) { c1[j] = dpp_ror1(g[j]); c2[j] = dpp_ror2(g[j]); }
;                     f32x4 p1 = c1, p2 = c2;
;                     if (m == 0 && smp) {
;                         const float* sp = st + ((size_t)(seg - 512) * 2) * FF + col + 4 * n; const f32x4 s0 = *(const f32x4*)sp, s1 = *(const f32x4*)(sp + FF);
; #pragma unroll
;                         for (int j = 0; j < 4; ++j) { p1[j] = (fr == 0) ? s1[j] : c1[j]; p2[j] = (fr == 0) ? s0[j] : ((fr == 1) ? s1[j] : c2[j]); }
;                     }
;                     if (m > 0) {
; #pragma unroll
;                         for (int j = 0; j < 4; ++j) { p1[j] = (fr == 0) ? q1[n][j] : c1[j]; p2[j] = (fr < 2) ? q2[n][j] : c2[j]; }
;                     }
;                     q1[n] = c1; q2[n] = c2;
;                     const f32x4 ww0 = n ? w0.b : w0.a, ww1 = n ? w1.b : w1.a, ww2 = n ? w2.b : w2.a, wb = n ? bb.b : bb.a;
;                     const f32x4 y = ww0 * p2 + ww1 * p1 + ww2 * g + wb;
; #pragma unroll
;                     for (int j = 0; j < 4; ++j) hh[n][j] = silu_f(y[j]) * v[j];
;                 }
;                 if (m == 0 && fr < 2 && !smp) {
;                     float* o = SG0 + ((size_t)seg * 2 + fr) * FF + col; *(f32x4*)o = acc[ai][1][m][0]; *(f32x4*)(o + 4) = acc[ai][1][m][1];
;                     float* o2 = SV0 + ((size_t)seg * 2 + fr) * FF + col; *(f32x4*)o2 = acc[ai][0][m][0]; *(f32x4*)(o2 + 4) = acc[ai][0][m][1];
;                 } else {
;                     u32x4 w; w.x = pk2(hh[0][0], hh[0][1]); w.y = pk2(hh[0][2], hh[0][3]); w.z = pk2(hh[1][0], hh[1][1]); w.w = pk2(hh[1][2], hh[1][3]);
;                     *(u32x4*)(H + (size_t)row * FF + col) = w;
	global_store_dwordx4 v[138:139], v[134:137], off nt
	v_pk_mul_f32 v[126:127], v[126:127], v[140:141]
	v_mov_b32_dpp v144, v120 row_ror:1 row_mask:0xf bank_mask:0xf
	v_mov_b32_dpp v146, v121 row_ror:1 row_mask:0xf bank_mask:0xf
	v_cndmask_b32_e64 v134, v145, v165, s[40:41]
	v_cndmask_b32_e64 v135, v147, v167, s[40:41]
	v_pk_mul_f32 v[122:123], v[122:123], v[126:127]
	v_pk_mul_f32 v[126:127], v[128:129], v[142:143]
	v_mov_b32_dpp v141, v118 row_ror:2 row_mask:0xf bank_mask:0xf
	v_mov_b32_dpp v143, v119 row_ror:2 row_mask:0xf bank_mask:0xf
	v_pk_mul_f32 v[134:135], v[84:85], v[134:135]
	v_cndmask_b32_e64 v138, v144, v164, s[36:37]
	v_cndmask_b32_e64 v139, v146, v166, s[36:37]
	v_mov_b32_dpp v140, v118 row_ror:1 row_mask:0xf bank_mask:0xf
	v_mov_b32_dpp v142, v119 row_ror:1 row_mask:0xf bank_mask:0xf
	v_cndmask_b32_e64 v128, v141, v153, s[40:41]
	v_cndmask_b32_e64 v129, v143, v163, s[40:41]
	v_pk_fma_f32 v[134:135], v[76:77], v[138:139], v[134:135]
	v_pk_mul_f32 v[128:129], v[82:83], v[128:129]
	v_cndmask_b32_e64 v136, v140, v152, s[36:37]
	v_cndmask_b32_e64 v137, v142, v162, s[36:37]
	v_pk_fma_f32 v[120:121], v[120:121], v[68:69], v[134:135]
	v_pk_fma_f32 v[128:129], v[74:75], v[136:137], v[128:129]
	v_pk_add_f32 v[120:121], v[72:73], v[120:121]
	v_pk_fma_f32 v[118:119], v[118:119], v[66:67], v[128:129]
	v_mul_f32_e32 v128, 0xbfb8aa3b, v121
	v_exp_f32_e32 v128, v128
	v_mul_f32_e32 v129, 0xbfb8aa3b, v120
	v_exp_f32_e32 v134, v129
	v_pk_add_f32 v[118:119], v[70:71], v[118:119]
	v_add_f32_e32 v128, 1.0, v128
	v_rcp_f32_e32 v129, v128
	v_add_f32_e32 v128, 1.0, v134
	v_mul_f32_e32 v134, 0xbfb8aa3b, v119
	v_exp_f32_e32 v134, v134
	v_mul_f32_e32 v135, 0xbfb8aa3b, v118
	v_exp_f32_e32 v136, v135
	v_rcp_f32_e32 v128, v128
	v_add_f32_e32 v134, 1.0, v134
	v_rcp_f32_e32 v135, v134
	v_add_f32_e32 v134, 1.0, v136
	v_rcp_f32_e32 v134, v134
	v_pk_mul_f32 v[120:121], v[120:121], v[128:129]
	v_pk_mul_f32 v[124:125], v[124:125], v[126:127]
	v_pk_mul_f32 v[120:121], v[116:117], v[120:121]
	v_pk_mul_f32 v[116:117], v[118:119], v[134:135]
	v_mov_b32_dpp v126, v88 row_ror:1 row_mask:0xf bank_mask:0xf
	v_pk_mul_f32 v[116:117], v[114:115], v[116:117]
	v_cvt_pk_bf16_f32 v114, v122, v123
	v_cvt_pk_bf16_f32 v116, v116, v117
	v_cvt_pk_bf16_f32 v117, v120, v121
	v_mov_b32_dpp v120, v86 row_ror:2 row_mask:0xf bank_mask:0xf
	v_mov_b32_dpp v121, v87 row_ror:2 row_mask:0xf bank_mask:0xf
	v_cvt_pk_bf16_f32 v115, v124, v125
	v_mov_b32_dpp v124, v86 row_ror:1 row_mask:0xf bank_mask:0xf
	v_mov_b32_dpp v125, v87 row_ror:1 row_mask:0xf bank_mask:0xf
	v_mov_b32_dpp v122, v88 row_ror:2 row_mask:0xf bank_mask:0xf
	v_mov_b32_dpp v123, v89 row_ror:2 row_mask:0xf bank_mask:0xf
	v_cndmask_b32_e64 v120, v120, v149, s[40:41]
	v_cndmask_b32_e64 v121, v121, v151, s[40:41]
	v_mov_b32_dpp v127, v89 row_ror:1 row_mask:0xf bank_mask:0xf
	v_cndmask_b32_e64 v122, v122, v169, s[40:41]
	v_cndmask_b32_e64 v123, v123, v171, s[40:41]
	v_cndmask_b32_e64 v124, v124, v148, s[36:37]
	v_cndmask_b32_e64 v125, v125, v150, s[36:37]
	v_pk_mul_f32 v[120:121], v[102:103], v[120:121]
	v_cndmask_b32_e64 v126, v126, v168, s[36:37]
	v_cndmask_b32_e64 v127, v127, v170, s[36:37]
	v_pk_mul_f32 v[122:123], v[104:105], v[122:123]
	v_pk_fma_f32 v[120:121], v[98:99], v[124:125], v[120:121]
	v_pk_fma_f32 v[122:123], v[100:101], v[126:127], v[122:123]
	v_pk_fma_f32 v[120:121], v[86:87], v[94:95], v[120:121]
	v_pk_fma_f32 v[122:123], v[88:89], v[96:97], v[122:123]
	v_pk_add_f32 v[120:121], v[90:91], v[120:121]
	v_pk_add_f32 v[122:123], v[92:93], v[122:123]
	v_mul_f32_e32 v124, 0xbfb8aa3b, v120
	v_mul_f32_e32 v125, 0xbfb8aa3b, v121
	v_exp_f32_e32 v124, v124
	v_exp_f32_e32 v125, v125
	v_mul_f32_e32 v126, 0xbfb8aa3b, v122
	v_mul_f32_e32 v127, 0xbfb8aa3b, v123
	v_exp_f32_e32 v126, v126
	v_exp_f32_e32 v127, v127
	v_add_f32_e32 v124, 1.0, v124
	v_add_f32_e32 v125, 1.0, v125
	v_or_b32_e32 v118, 32, v64
	v_rcp_f32_e32 v124, v124
	v_rcp_f32_e32 v125, v125
	v_add_f32_e32 v126, 1.0, v126
	v_add_f32_e32 v127, 1.0, v127
	v_mad_i64_i32 v[118:119], s[6:7], v118, s27, v[132:133]
	v_rcp_f32_e32 v126, v126
	v_rcp_f32_e32 v127, v127
	v_lshl_add_u64 v[118:119], v[118:119], 0, v[130:131]
	global_store_dwordx4 v[118:119], v[114:117], off nt
	v_or_b32_e32 v64, 48, v64
	v_mov_b32_dpp v118, v78 row_ror:1 row_mask:0xf bank_mask:0xf
	v_mov_b32_dpp v116, v80 row_ror:2 row_mask:0xf bank_mask:0xf
	v_mov_b32_dpp v117, v81 row_ror:2 row_mask:0xf bank_mask:0xf
	v_pk_mul_f32 v[114:115], v[120:121], v[124:125]
	v_mov_b32_dpp v120, v80 row_ror:1 row_mask:0xf bank_mask:0xf
	v_mov_b32_dpp v121, v81 row_ror:1 row_mask:0xf bank_mask:0xf
	v_cndmask_b32_e64 v116, v116, v145, s[40:41]
	v_cndmask_b32_e64 v117, v117, v147, s[40:41]
	v_pk_mul_f32 v[110:111], v[110:111], v[114:115]
	v_pk_mul_f32 v[114:115], v[122:123], v[126:127]
	v_pk_mul_f32 v[116:117], v[84:85], v[116:117]
	v_cndmask_b32_e64 v120, v120, v144, s[36:37]
	v_cndmask_b32_e64 v121, v121, v146, s[36:37]
	v_pk_mul_f32 v[112:113], v[112:113], v[114:115]
	v_mov_b32_dpp v114, v78 row_ror:2 row_mask:0xf bank_mask:0xf
	v_mov_b32_dpp v115, v79 row_ror:2 row_mask:0xf bank_mask:0xf
	v_pk_fma_f32 v[116:117], v[76:77], v[120:121], v[116:117]
	v_mov_b32_dpp v119, v79 row_ror:1 row_mask:0xf bank_mask:0xf
	v_cndmask_b32_e64 v114, v114, v141, s[40:41]
	v_cndmask_b32_e64 v115, v115, v143, s[40:41]
	v_pk_fma_f32 v[116:117], v[80:81], v[68:69], v[116:117]
	v_pk_mul_f32 v[114:115], v[82:83], v[114:115]
	v_cndmask_b32_e64 v118, v118, v140, s[36:37]
	v_cndmask_b32_e64 v119, v119, v142, s[36:37]
	v_pk_add_f32 v[116:117], v[72:73], v[116:117]
	v_pk_fma_f32 v[114:115], v[74:75], v[118:119], v[114:115]
	v_mul_f32_e32 v118, 0xbfb8aa3b, v117
	v_exp_f32_e32 v118, v118
	v_mul_f32_e32 v119, 0xbfb8aa3b, v116
	v_exp_f32_e32 v120, v119
	v_pk_fma_f32 v[114:115], v[78:79], v[66:67], v[114:115]
	v_add_f32_e32 v118, 1.0, v118
	v_pk_add_f32 v[114:115], v[70:71], v[114:115]
	v_rcp_f32_e32 v119, v118
	v_add_f32_e32 v118, 1.0, v120
	v_mul_f32_e32 v120, 0xbfb8aa3b, v115
	v_exp_f32_e32 v120, v120
	v_mul_f32_e32 v121, 0xbfb8aa3b, v114
	v_exp_f32_e32 v122, v121
	v_rcp_f32_e32 v118, v118
	v_add_f32_e32 v120, 1.0, v120
	v_rcp_f32_e32 v121, v120
	v_add_f32_e32 v120, 1.0, v122
	v_rcp_f32_e32 v120, v120
	v_pk_mul_f32 v[116:117], v[116:117], v[118:119]
	s_nop 0
	v_pk_mul_f32 v[116:117], v[108:109], v[116:117]
	v_pk_mul_f32 v[108:109], v[114:115], v[120:121]
	s_nop 0
	v_pk_mul_f32 v[108:109], v[106:107], v[108:109]
	v_cvt_pk_bf16_f32 v106, v110, v111
	v_mad_i64_i32 v[110:111], s[6:7], v64, s27, v[132:133]
	v_cvt_pk_bf16_f32 v107, v112, v113
	v_cvt_pk_bf16_f32 v108, v108, v109
	v_cvt_pk_bf16_f32 v109, v116, v117
	v_lshl_add_u64 v[110:111], v[110:111], 0, v[130:131]
	global_store_dwordx4 v[110:111], v[106:109], off nt
	s_and_saveexec_b64 s[6:7], s[44:45]
	s_cbranch_execz .LBB0_103
; DI void rowinfo(int row, int& s, int& b, int& t) { if (row < MP) { s = 0; b = row >> 12; t = row & 4095; } else { const int r = row - MP; s = 1; b = r >> 6; t = r & 63; } }
;     DI void operator()(const f32x4 (&acc)[2][2][4][2], const Unit& u, int wr, int wc, int fr, int fq) const {
;     ...
;                 if (m == 3 && fr >= 14) {
;                     float* o = SGL + ((size_t)seg * 2 + (fr - 14)) * FF + col; *(f32x4*)o = acc[ai][1][m][0]; *(f32x4*)(o + 4) = acc[ai][1][m][1];
;                     int s, b, t; rowinfo(row, s, b, t); const int L = s ? 64 : 4096;
;                     if (t >= L - 2) { float* os = out + (s ? O_FFNS : O_FFNP) + ((size_t)(layer * 8 + b) * 2 + (t - (L - 2))) * FF + col; *(f32x4*)os = acc[ai][1][m][0]; *(f32x4*)(os + 4) = acc[ai][1][m][1]; }
	v_lshl_add_u64 v[106:107], s[0:1], 0, v[204:205]
	v_mov_b64_e32 v[108:109], s[62:63]
	v_mad_u64_u32 v[108:109], s[0:1], v106, s90, v[108:109]
	v_mad_i32_i24 v109, v107, s90, v109
	v_lshl_add_u64 v[106:107], v[210:211], 2, v[108:109]
	v_cmp_gt_i32_e32 vcc, s81, v64
	global_store_dwordx4 v[106:107], v[86:89], off nt
	global_store_dwordx4 v[106:107], v[78:81], off offset:16 nt
	v_cndmask_b32_e32 v106, 63, v229, vcc
	v_and_b32_e32 v106, v106, v64
	v_mov_b32_e32 v64, 0xffe
	v_cndmask_b32_e32 v107, 62, v64, vcc
	v_cmp_ge_u32_e64 s[0:1], v106, v107
	s_and_b64 exec, exec, s[0:1]
	s_cbranch_execz .LBB0_103
	s_addk_i32 s10, 0x8000
	s_lshr_b32 s0, s10, 6
	s_ashr_i32 s1, s30, 6
	v_mov_b32_e32 v64, s0
	v_mov_b32_e32 v108, s1
	v_cndmask_b32_e32 v110, v64, v108, vcc
	v_mov_b32_e32 v64, 0x19120000
	v_mov_b32_e32 v108, 0x19070000
	v_cndmask_b32_e32 v64, v64, v108, vcc
	v_lshl_add_u64 v[108:109], s[64:65], 0, v[64:65]
	v_add_u32_e32 v64, s70, v110
	v_sub_u32_e32 v106, v106, v107
	v_lshl_add_u32 v64, v64, 1, v106
	v_mad_i64_i32 v[106:107], s[0:1], v64, s90, v[108:109]
	v_lshl_add_u64 v[106:107], v[210:211], 2, v[106:107]
	global_store_dwordx4 v[106:107], v[86:89], off nt
	global_store_dwordx4 v[106:107], v[78:81], off offset:16 nt

; DI unsigned pk2(float lo, float hi) { f32x2 v = {lo, hi}; bf16x2_t b = __builtin_convertvector(v, bf16x2_t); return __builtin_bit_cast(unsigned, b); }
; DI float dpp_ror1(float v) { return __int_as_float(__builtin_amdgcn_mov_dpp(__float_as_int(v), 0x121, 0xf, 0xf, false)); }
;     DI void operator()(const f32x4 (&acc)[2][2][4][2], const Unit& u, int wr, int wc, int fr, int fq) const {
;     ...
;                 const int row = seg * 64 + m * 16 + fr;
;                 f32x4 hh[2];
; #pragma unroll
;                 for (int n = 0; n < 2; ++n) {
;                     const f32x4 g = acc[ai][1][m][n], v = acc[ai][0][m][n];
;                     f32x4 c1, c2;
; #pragma unroll
;                     for (int j = 0; j < 4; ++j) { c1[j] = dpp_ror1(g[j]); c2[j] = dpp_ror2(g[j]); }
;                     f32x4 p1 = c1, p2 = c2;
;                     if (m == 0 && smp) {
;                         const float* sp = st + ((size_t)(seg - 512) * 2) * FF + col + 4 * n; const f32x4 s0 = *(const f32x4*)sp, s1 = *(const f32x4*)(sp + FF);
; #pragma unroll
;                         for (int j = 0; j < 4; ++j) { p1[j] = (fr == 0) ? s1[j] : c1[j]; p2[j] = (fr == 0) ? s0[j] : ((fr == 1) ? s1[j] : c2[j]); }
;                     }
;                     if (m > 0) {
; #pragma unroll
;                         for (int j = 0; j < 4; ++j) { p1[j] = (fr == 0) ? q1[n][j] : c1[j]; p2[j] = (fr < 2) ? q2[n][j] : c2[j]; }
;                     }
;                     q1[n] = c1; q2[n] = c2;
;                     const f32x4 ww0 = n ? w0.b : w0.a, ww1 = n ? w1.b : w1.a, ww2 = n ? w2.b : w2.a, wb = n ? bb.b : bb.a;
;                     const f32x4 y = ww0 * p2 + ww1 * p1 + ww2 * g + wb;
; #pragma unroll
;                     for (int j = 0; j < 4; ++j) hh[n][j] = silu_f(y[j]) * v[j];
;                 }
;                 if (m == 0 && fr < 2 && !smp) {
;                     float* o = SG0 + ((size_t)seg * 2 + fr) * FF + col; *(f32x4*)o = acc[ai][1][m][0]; *(f32x4*)(o + 4) = acc[ai][1][m][1];
;                     float* o2 = SV0 + ((size_t)seg * 2 + fr) * FF + col; *(f32x4*)o2 = acc[ai][0][m][0]; *(f32x4*)(o2 + 4) = acc[ai][0][m][1];
;                 } else {
;                     u32x4 w; w.x = pk2(hh[0][0], hh[0][1]); w.y = pk2(hh[0][2], hh[0][3]); w.z = pk2(hh[1][0], hh[1][1]); w.w = pk2(hh[1][2], hh[1][3]);
;                     *(u32x4*)(H + (size_t)row * FF + col) = w;
.LBB0_111:
	s_add_i32 s6, s30, 2
	s_ashr_i32 s7, s6, 31
	s_lshl_b64 s[0:1], s[6:7], 1
	s_and_saveexec_b64 s[10:11], s[4:5]
	s_xor_b64 s[4:5], exec, s[10:11]
	s_cbranch_execz .LBB0_113
	v_lshl_add_u64 v[114:115], s[0:1], 0, v[202:203]
	v_mov_b64_e32 v[116:117], s[22:23]
	v_mad_u64_u32 v[116:117], s[10:11], v114, s90, v[116:117]
	v_mad_i32_i24 v117, v115, s90, v117
	v_lshl_add_u64 v[116:117], v[116:117], 0, v[212:213]
	global_store_dwordx4 v[116:117], v[60:63], off nt
	global_store_dwordx4 v[116:117], v[52:55], off offset:16 nt
	v_mov_b64_e32 v[116:117], s[94:95]
	v_mad_u64_u32 v[116:117], s[10:11], v114, s90, v[116:117]
	v_mad_i32_i24 v117, v115, s90, v117
	v_lshl_add_u64 v[114:115], v[116:117], 0, v[212:213]
	global_store_dwordx4 v[114:115], v[56:59], off nt
	global_store_dwordx4 v[114:115], v[48:51], off offset:16 nt
.LBB0_113:
	s_or_saveexec_b64 s[4:5], s[4:5]
	s_lshl_b32 s7, s6, 6
	v_or_b32_e32 v64, s7, v202
	s_xor_b64 exec, exec, s[4:5]
	s_cbranch_execz .LBB0_115
	v_pk_mul_f32 v[114:115], v[98:99], v[114:115]
	v_pk_mul_f32 v[116:117], v[100:101], v[116:117]
	v_pk_fma_f32 v[114:115], v[102:103], v[118:119], v[114:115]
	v_pk_fma_f32 v[116:117], v[104:105], v[120:121], v[116:117]
	v_pk_fma_f32 v[60:61], v[60:61], v[94:95], v[114:115]
	v_pk_fma_f32 v[62:63], v[62:63], v[96:97], v[116:117]
	v_pk_add_f32 v[60:61], v[90:91], v[60:61]
	v_pk_add_f32 v[62:63], v[92:93], v[62:63]
	v_mul_f32_e32 v114, 0xbfb8aa3b, v60
	v_mul_f32_e32 v115, 0xbfb8aa3b, v61
	v_exp_f32_e32 v114, v114
	v_exp_f32_e32 v115, v115
	v_mul_f32_e32 v116, 0xbfb8aa3b, v62
	v_mul_f32_e32 v117, 0xbfb8aa3b, v63
	v_exp_f32_e32 v116, v116
	v_exp_f32_e32 v117, v117
	v_add_f32_e32 v114, 1.0, v114
	v_add_f32_e32 v115, 1.0, v115
	v_rcp_f32_e32 v114, v114
	v_rcp_f32_e32 v115, v115
	v_add_f32_e32 v116, 1.0, v116
	v_add_f32_e32 v117, 1.0, v117
	v_rcp_f32_e32 v116, v116
	v_rcp_f32_e32 v117, v117
	v_pk_mul_f32 v[60:61], v[60:61], v[114:115]
	v_pk_mul_f32 v[114:115], v[74:75], v[122:123]
	v_pk_mul_f32 v[56:57], v[56:57], v[60:61]
	v_pk_mul_f32 v[60:61], v[62:63], v[116:117]
	v_pk_mul_f32 v[62:63], v[76:77], v[124:125]
	v_pk_fma_f32 v[114:115], v[82:83], v[126:127], v[114:115]
	v_pk_fma_f32 v[62:63], v[84:85], v[128:129], v[62:63]
	v_pk_fma_f32 v[52:53], v[52:53], v[66:67], v[114:115]
	v_pk_fma_f32 v[54:55], v[54:55], v[68:69], v[62:63]
	v_pk_add_f32 v[52:53], v[70:71], v[52:53]
	v_pk_add_f32 v[54:55], v[72:73], v[54:55]
	v_mul_f32_e32 v115, 0xbfb8aa3b, v52
	v_mul_f32_e32 v62, 0xbfb8aa3b, v55
	v_exp_f32_e32 v62, v62
	v_mul_f32_e32 v63, 0xbfb8aa3b, v54
	v_exp_f32_e32 v114, v63
	v_exp_f32_e32 v116, v115
	v_add_f32_e32 v62, 1.0, v62
	v_rcp_f32_e32 v63, v62
	v_add_f32_e32 v62, 1.0, v114
	v_mul_f32_e32 v114, 0xbfb8aa3b, v53
	v_exp_f32_e32 v114, v114
	v_rcp_f32_e32 v62, v62
	v_pk_mul_f32 v[58:59], v[58:59], v[60:61]
	v_add_f32_e32 v114, 1.0, v114
	v_rcp_f32_e32 v115, v114
	v_add_f32_e32 v114, 1.0, v116
	v_rcp_f32_e32 v114, v114
	v_pk_mul_f32 v[54:55], v[54:55], v[62:63]
	s_nop 0
	v_pk_mul_f32 v[54:55], v[50:51], v[54:55]
	v_pk_mul_f32 v[50:51], v[52:53], v[114:115]
	v_mov_b64_e32 v[52:53], s[54:55]
	v_pk_mul_f32 v[50:51], v[48:49], v[50:51]
	v_mad_i64_i32 v[52:53], s[10:11], v64, s89, v[52:53]
	v_cvt_pk_bf16_f32 v48, v56, v57
	v_cvt_pk_bf16_f32 v49, v58, v59
	v_cvt_pk_bf16_f32 v50, v50, v51
	v_cvt_pk_bf16_f32 v51, v54, v55
	v_lshl_add_u64 v[52:53], v[210:211], 1, v[52:53]
	global_store_dwordx4 v[52:53], v[48:51], off nt
.LBB0_115:
	s_or_b64 exec, exec, s[4:5]
	v_mov_b32_dpp v57, v44 row_ror:2 row_mask:0xf bank_mask:0xf
	v_mov_b32_dpp v59, v45 row_ror:2 row_mask:0xf bank_mask:0xf
	v_mov_b32_dpp v56, v44 row_ror:1 row_mask:0xf bank_mask:0xf
	v_mov_b32_dpp v58, v45 row_ror:1 row_mask:0xf bank_mask:0xf
	v_cndmask_b32_e64 v48, v57, v86, s[40:41]
	v_cndmask_b32_e64 v49, v59, v87, s[40:41]
	v_mov_b32_dpp v61, v46 row_ror:2 row_mask:0xf bank_mask:0xf
	v_mov_b32_dpp v63, v47 row_ror:2 row_mask:0xf bank_mask:0xf
	v_cndmask_b32_e64 v52, v56, v78, s[36:37]
	v_cndmask_b32_e64 v53, v58, v79, s[36:37]
	v_pk_mul_f32 v[48:49], v[102:103], v[48:49]
	v_mov_b32_dpp v60, v46 row_ror:1 row_mask:0xf bank_mask:0xf
	v_mov_b32_dpp v62, v47 row_ror:1 row_mask:0xf bank_mask:0xf
	v_cndmask_b32_e64 v50, v61, v88, s[40:41]
	v_cndmask_b32_e64 v51, v63, v89, s[40:41]
	v_pk_fma_f32 v[48:49], v[98:99], v[52:53], v[48:49]
	v_cndmask_b32_e64 v54, v60, v80, s[36:37]
	v_cndmask_b32_e64 v55, v62, v81, s[36:37]
	v_pk_mul_f32 v[50:51], v[104:105], v[50:51]
	v_pk_fma_f32 v[44:45], v[44:45], v[94:95], v[48:49]
	v_pk_fma_f32 v[50:51], v[100:101], v[54:55], v[50:51]
	v_pk_add_f32 v[44:45], v[90:91], v[44:45]
	v_pk_fma_f32 v[46:47], v[46:47], v[96:97], v[50:51]
	v_mul_f32_e32 v48, 0xbfb8aa3b, v44
	v_mul_f32_e32 v49, 0xbfb8aa3b, v45
	v_exp_f32_e32 v48, v48
	v_exp_f32_e32 v49, v49
	v_pk_add_f32 v[46:47], v[92:93], v[46:47]
	v_mov_b32_dpp v81, v38 row_ror:2 row_mask:0xf bank_mask:0xf
	v_mul_f32_e32 v50, 0xbfb8aa3b, v46
	v_mul_f32_e32 v51, 0xbfb8aa3b, v47
	v_exp_f32_e32 v50, v50
	v_exp_f32_e32 v51, v51
	v_add_f32_e32 v48, 1.0, v48
	v_add_f32_e32 v49, 1.0, v49
	v_rcp_f32_e32 v48, v48
	v_rcp_f32_e32 v49, v49
	v_add_f32_e32 v50, 1.0, v50
	v_add_f32_e32 v51, 1.0, v51
	v_rcp_f32_e32 v50, v50
	v_rcp_f32_e32 v51, v51
	v_mov_b32_dpp v87, v39 row_ror:2 row_mask:0xf bank_mask:0xf
	v_pk_mul_f32 v[44:45], v[44:45], v[48:49]
	v_mov_b32_dpp v80, v38 row_ror:1 row_mask:0xf bank_mask:0xf
	v_mov_b32_dpp v86, v39 row_ror:1 row_mask:0xf bank_mask:0xf
	v_cndmask_b32_e64 v48, v81, v112, s[40:41]
	v_cndmask_b32_e64 v49, v87, v113, s[40:41]
	v_mov_b32_dpp v55, v36 row_ror:2 row_mask:0xf bank_mask:0xf
	v_mov_b32_dpp v79, v37 row_ror:2 row_mask:0xf bank_mask:0xf
; DI unsigned pk2(float lo, float hi) { f32x2 v = {lo, hi}; bf16x2_t b = __builtin_convertvector(v, bf16x2_t); return __builtin_bit_cast(unsigned, b); }
; DI float dpp_ror1(float v) { return __int_as_float(__builtin_amdgcn_mov_dpp(__float_as_int(v), 0x121, 0xf, 0xf, false)); }
; DI float dpp_ror2(float v) { return __int_as_float(__builtin_amdgcn_mov_dpp(__float_as_int(v), 0x122, 0xf, 0xf, false)); }
;     DI void operator()(const f32x4 (&acc)[2][2][4][2], const Unit& u, int wr, int wc, int fr, int fq) const {
;     ...
;                     const f32x4 g = acc[ai][1][m][n], v = acc[ai][0][m][n];
;                     f32x4 c1, c2;
; #pragma unroll
;                     for (int j = 0; j < 4; ++j) { c1[j] = dpp_ror1(g[j]); c2[j] = dpp_ror2(g[j]); }
;                     f32x4 p1 = c1, p2 = c2;
;                     if (m == 0 && smp) {
;                         const float* sp = st + ((size_t)(seg - 512) * 2) * FF + col + 4 * n; const f32x4 s0 = *(const f32x4*)sp, s1 = *(const f32x4*)(sp + FF);
; #pragma unroll
;                         for (int j = 0; j < 4; ++j) { p1[j] = (fr == 0) ? s1[j] : c1[j]; p2[j] = (fr == 0) ? s0[j] : ((fr == 1) ? s1[j] : c2[j]); }
;                     }
;                     if (m > 0) {
; #pragma unroll
;                         for (int j = 0; j < 4; ++j) { p1[j] = (fr == 0) ? q1[n][j] : c1[j]; p2[j] = (fr < 2) ? q2[n][j] : c2[j]; }
;                     }
;                     q1[n] = c1; q2[n] = c2;
;                     const f32x4 ww0 = n ? w0.b : w0.a, ww1 = n ? w1.b : w1.a, ww2 = n ? w2.b : w2.a, wb = n ? bb.b : bb.a;
;                     const f32x4 y = ww0 * p2 + ww1 * p1 + ww2 * g + wb;
; #pragma unroll
;                     for (int j = 0; j < 4; ++j) hh[n][j] = silu_f(y[j]) * v[j];
;                 }
;                 if (m == 0 && fr < 2 && !smp) {
;                     float* o = SG0 + ((size_t)seg * 2 + fr) * FF + col; *(f32x4*)o = acc[ai][1][m][0]; *(f32x4*)(o + 4) = acc[ai][1][m][1];
;                     float* o2 = SV0 + ((size_t)seg * 2 + fr) * FF + col; *(f32x4*)o2 = acc[ai][0][m][0]; *(f32x4*)(o2 + 4) = acc[ai][0][m][1];
;                 } else {
;                     u32x4 w; w.x = pk2(hh[0][0], hh[0][1]); w.y = pk2(hh[0][2], hh[0][3]); w.z = pk2(hh[1][0], hh[1][1]); w.w = pk2(hh[1][2], hh[1][3]);
;                     *(u32x4*)(H + (size_t)row * FF + col) = w;
	v_pk_mul_f32 v[48:49], v[84:85], v[48:49]
	v_cndmask_b32_e64 v52, v80, v108, s[36:37]
	v_cndmask_b32_e64 v53, v86, v109, s[36:37]
	v_pk_mul_f32 v[40:41], v[40:41], v[44:45]
	v_pk_mul_f32 v[44:45], v[46:47], v[50:51]
	v_mov_b32_dpp v54, v36 row_ror:1 row_mask:0xf bank_mask:0xf
	v_mov_b32_dpp v78, v37 row_ror:1 row_mask:0xf bank_mask:0xf
	v_cndmask_b32_e64 v46, v55, v110, s[40:41]
	v_cndmask_b32_e64 v47, v79, v111, s[40:41]
	v_pk_fma_f32 v[48:49], v[76:77], v[52:53], v[48:49]
	v_pk_mul_f32 v[46:47], v[82:83], v[46:47]
	v_cndmask_b32_e64 v50, v54, v106, s[36:37]
	v_cndmask_b32_e64 v51, v78, v107, s[36:37]
	v_pk_fma_f32 v[38:39], v[38:39], v[68:69], v[48:49]
	v_pk_fma_f32 v[46:47], v[74:75], v[50:51], v[46:47]
	v_pk_add_f32 v[38:39], v[72:73], v[38:39]
	v_pk_fma_f32 v[36:37], v[36:37], v[66:67], v[46:47]
	v_mul_f32_e32 v46, 0xbfb8aa3b, v39
	v_exp_f32_e32 v46, v46
	v_mul_f32_e32 v47, 0xbfb8aa3b, v38
	v_exp_f32_e32 v48, v47
	v_pk_add_f32 v[36:37], v[70:71], v[36:37]
	v_add_f32_e32 v46, 1.0, v46
	v_rcp_f32_e32 v47, v46
	v_add_f32_e32 v46, 1.0, v48
	v_mul_f32_e32 v48, 0xbfb8aa3b, v37
	v_exp_f32_e32 v48, v48
	v_mul_f32_e32 v49, 0xbfb8aa3b, v36
	v_exp_f32_e32 v50, v49
	v_rcp_f32_e32 v46, v46
	v_add_f32_e32 v48, 1.0, v48
	v_rcp_f32_e32 v49, v48
	v_add_f32_e32 v48, 1.0, v50
	v_rcp_f32_e32 v48, v48
	v_pk_mul_f32 v[38:39], v[38:39], v[46:47]
	v_mov_b32_dpp v51, v29 row_ror:2 row_mask:0xf bank_mask:0xf
	v_pk_mul_f32 v[38:39], v[34:35], v[38:39]
	v_pk_mul_f32 v[34:35], v[36:37], v[48:49]
	v_mov_b32_dpp v49, v28 row_ror:2 row_mask:0xf bank_mask:0xf
	v_pk_mul_f32 v[32:33], v[32:33], v[34:35]
	v_pk_mul_f32 v[42:43], v[42:43], v[44:45]
	v_or_b32_e32 v44, 16, v64
	v_cvt_pk_bf16_f32 v34, v40, v41
	v_cvt_pk_bf16_f32 v36, v32, v33
	v_mov_b64_e32 v[32:33], s[54:55]
	v_mov_b32_dpp v48, v28 row_ror:1 row_mask:0xf bank_mask:0xf
	v_mov_b32_dpp v50, v29 row_ror:1 row_mask:0xf bank_mask:0xf
	v_mov_b32_dpp v53, v30 row_ror:2 row_mask:0xf bank_mask:0xf
	v_mov_b32_dpp v89, v31 row_ror:2 row_mask:0xf bank_mask:0xf
	v_cndmask_b32_e64 v40, v49, v57, s[40:41]
	v_cndmask_b32_e64 v41, v51, v59, s[40:41]
	v_cvt_pk_bf16_f32 v35, v42, v43
	v_cvt_pk_bf16_f32 v37, v38, v39
	v_mad_i64_i32 v[38:39], s[4:5], v44, s89, v[32:33]
	v_mov_b32_dpp v52, v30 row_ror:1 row_mask:0xf bank_mask:0xf
	v_mov_b32_dpp v88, v31 row_ror:1 row_mask:0xf bank_mask:0xf
	v_cndmask_b32_e64 v42, v53, v61, s[40:41]
	v_cndmask_b32_e64 v43, v89, v63, s[40:41]
	v_cndmask_b32_e64 v44, v48, v56, s[36:37]
	v_cndmask_b32_e64 v45, v50, v58, s[36:37]
	v_pk_mul_f32 v[40:41], v[102:103], v[40:41]
	v_cndmask_b32_e64 v46, v52, v60, s[36:37]
	v_cndmask_b32_e64 v47, v88, v62, s[36:37]
	v_pk_mul_f32 v[42:43], v[104:105], v[42:43]
	v_pk_fma_f32 v[40:41], v[98:99], v[44:45], v[40:41]
	v_pk_fma_f32 v[42:43], v[100:101], v[46:47], v[42:43]
	v_pk_fma_f32 v[28:29], v[28:29], v[94:95], v[40:41]
	v_pk_fma_f32 v[30:31], v[30:31], v[96:97], v[42:43]
	v_pk_add_f32 v[28:29], v[90:91], v[28:29]
	v_pk_add_f32 v[30:31], v[92:93], v[30:31]
	v_mul_f32_e32 v40, 0xbfb8aa3b, v28
	v_mul_f32_e32 v41, 0xbfb8aa3b, v29
	v_exp_f32_e32 v40, v40
	v_exp_f32_e32 v41, v41
	v_mul_f32_e32 v42, 0xbfb8aa3b, v30
	v_mul_f32_e32 v43, 0xbfb8aa3b, v31
	v_exp_f32_e32 v42, v42
	v_exp_f32_e32 v43, v43
	v_add_f32_e32 v40, 1.0, v40
	v_add_f32_e32 v41, 1.0, v41
	v_rcp_f32_e32 v40, v40
	v_rcp_f32_e32 v41, v41
	v_add_f32_e32 v42, 1.0, v42
	v_add_f32_e32 v43, 1.0, v43
	v_rcp_f32_e32 v42, v42
	v_rcp_f32_e32 v43, v43
	v_lshl_add_u64 v[38:39], v[38:39], 0, v[130:131]
	v_mov_b32_dpp v45, v22 row_ror:2 row_mask:0xf bank_mask:0xf
	v_mov_b32_dpp v47, v23 row_ror:2 row_mask:0xf bank_mask:0xf
	global_store_dwordx4 v[38:39], v[34:37], off nt
	v_pk_mul_f32 v[28:29], v[28:29], v[40:41]
	v_mov_b32_dpp v44, v22 row_ror:1 row_mask:0xf bank_mask:0xf
	v_mov_b32_dpp v46, v23 row_ror:1 row_mask:0xf bank_mask:0xf
	v_cndmask_b32_e64 v34, v45, v81, s[40:41]
	v_cndmask_b32_e64 v35, v47, v87, s[40:41]
	v_pk_mul_f32 v[24:25], v[24:25], v[28:29]
	v_pk_mul_f32 v[28:29], v[30:31], v[42:43]
	v_mov_b32_dpp v41, v20 row_ror:2 row_mask:0xf bank_mask:0xf
	v_mov_b32_dpp v43, v21 row_ror:2 row_mask:0xf bank_mask:0xf
	v_pk_mul_f32 v[34:35], v[84:85], v[34:35]
	v_cndmask_b32_e64 v38, v44, v80, s[36:37]
	v_cndmask_b32_e64 v39, v46, v86, s[36:37]
	v_mov_b32_dpp v40, v20 row_ror:1 row_mask:0xf bank_mask:0xf
	v_mov_b32_dpp v42, v21 row_ror:1 row_mask:0xf bank_mask:0xf
	v_cndmask_b32_e64 v30, v41, v55, s[40:41]
	v_cndmask_b32_e64 v31, v43, v79, s[40:41]
	v_pk_fma_f32 v[34:35], v[76:77], v[38:39], v[34:35]
	v_pk_mul_f32 v[30:31], v[82:83], v[30:31]
	v_cndmask_b32_e64 v36, v40, v54, s[36:37]
	v_cndmask_b32_e64 v37, v42, v78, s[36:37]
	v_pk_fma_f32 v[22:23], v[22:23], v[68:69], v[34:35]
	v_pk_fma_f32 v[30:31], v[74:75], v[36:37], v[30:31]
	v_pk_add_f32 v[22:23], v[72:73], v[22:23]
	v_pk_fma_f32 v[20:21], v[20:21], v[66:67], v[30:31]
	v_mul_f32_e32 v30, 0xbfb8aa3b, v23
	v_exp_f32_e32 v30, v30
	v_mul_f32_e32 v31, 0xbfb8aa3b, v22
	v_exp_f32_e32 v34, v31
	v_pk_add_f32 v[20:21], v[70:71], v[20:21]
	v_add_f32_e32 v30, 1.0, v30
	v_rcp_f32_e32 v31, v30
	v_add_f32_e32 v30, 1.0, v34
	v_mul_f32_e32 v34, 0xbfb8aa3b, v21
	v_exp_f32_e32 v34, v34
	v_mul_f32_e32 v35, 0xbfb8aa3b, v20
	v_exp_f32_e32 v36, v35
	v_rcp_f32_e32 v30, v30
	v_add_f32_e32 v34, 1.0, v34
	v_rcp_f32_e32 v35, v34
	v_add_f32_e32 v34, 1.0, v36
	v_rcp_f32_e32 v34, v34
	v_pk_mul_f32 v[22:23], v[22:23], v[30:31]
	v_pk_mul_f32 v[26:27], v[26:27], v[28:29]
	v_pk_mul_f32 v[22:23], v[18:19], v[22:23]
	v_pk_mul_f32 v[18:19], v[20:21], v[34:35]
; DI unsigned pk2(float lo, float hi) { f32x2 v = {lo, hi}; bf16x2_t b = __builtin_convertvector(v, bf16x2_t); return __builtin_bit_cast(unsigned, b); }
;     DI void operator()(const f32x4 (&acc)[2][2][4][2], const Unit& u, int wr, int wc, int fr, int fq) const {
;     ...
;                     const f32x4 g = acc[ai][1][m][n], v = acc[ai][0][m][n];
;                     f32x4 c1, c2;
; #pragma unroll
;                     for (int j = 0; j < 4; ++j) { c1[j] = dpp_ror1(g[j]); c2[j] = dpp_ror2(g[j]); }
;                     f32x4 p1 = c1, p2 = c2;
;                     if (m == 0 && smp) {
;                         const float* sp = st + ((size_t)(seg - 512) * 2) * FF + col + 4 * n; const f32x4 s0 = *(const f32x4*)sp, s1 = *(const f32x4*)(sp + FF);
; #pragma unroll
;                         for (int j = 0; j < 4; ++j) { p1[j] = (fr == 0) ? s1[j] : c1[j]; p2[j] = (fr == 0) ? s0[j] : ((fr == 1) ? s1[j] : c2[j]); }
;                     }
;                     if (m > 0) {
; #pragma unroll
;                         for (int j = 0; j < 4; ++j) { p1[j] = (fr == 0) ? q1[n][j] : c1[j]; p2[j] = (fr < 2) ? q2[n][j] : c2[j]; }
;                     }
;                     q1[n] = c1; q2[n] = c2;
;                     const f32x4 ww0 = n ? w0.b : w0.a, ww1 = n ? w1.b : w1.a, ww2 = n ? w2.b : w2.a, wb = n ? bb.b : bb.a;
;                     const f32x4 y = ww0 * p2 + ww1 * p1 + ww2 * g + wb;
; #pragma unroll
;                     for (int j = 0; j < 4; ++j) hh[n][j] = silu_f(y[j]) * v[j];
;                 }
;                 if (m == 0 && fr < 2 && !smp) {
;                     float* o = SG0 + ((size_t)seg * 2 + fr) * FF + col; *(f32x4*)o = acc[ai][1][m][0]; *(f32x4*)(o + 4) = acc[ai][1][m][1];
;                     float* o2 = SV0 + ((size_t)seg * 2 + fr) * FF + col; *(f32x4*)o2 = acc[ai][0][m][0]; *(f32x4*)(o2 + 4) = acc[ai][0][m][1];
;                 } else {
;                     u32x4 w; w.x = pk2(hh[0][0], hh[0][1]); w.y = pk2(hh[0][2], hh[0][3]); w.z = pk2(hh[1][0], hh[1][1]); w.w = pk2(hh[1][2], hh[1][3]);
;                     *(u32x4*)(H + (size_t)row * FF + col) = w;
;                 }
;                 if (m == 3 && fr >= 14) {
;                     float* o = SGL + ((size_t)seg * 2 + (fr - 14)) * FF + col; *(f32x4*)o = acc[ai][1][m][0]; *(f32x4*)(o + 4) = acc[ai][1][m][1];
;                     int s, b, t; rowinfo(row, s, b, t); const int L = s ? 64 : 4096;
	v_mov_b32_dpp v28, v6 row_ror:1 row_mask:0xf bank_mask:0xf
	v_pk_mul_f32 v[18:19], v[16:17], v[18:19]
	v_cvt_pk_bf16_f32 v16, v24, v25
	v_cvt_pk_bf16_f32 v18, v18, v19
	v_cvt_pk_bf16_f32 v19, v22, v23
	v_mov_b32_dpp v22, v4 row_ror:2 row_mask:0xf bank_mask:0xf
	v_mov_b32_dpp v23, v5 row_ror:2 row_mask:0xf bank_mask:0xf
	v_cvt_pk_bf16_f32 v17, v26, v27
	v_mov_b32_dpp v26, v4 row_ror:1 row_mask:0xf bank_mask:0xf
	v_mov_b32_dpp v27, v5 row_ror:1 row_mask:0xf bank_mask:0xf
	v_mov_b32_dpp v24, v6 row_ror:2 row_mask:0xf bank_mask:0xf
	v_mov_b32_dpp v25, v7 row_ror:2 row_mask:0xf bank_mask:0xf
	v_cndmask_b32_e64 v22, v22, v49, s[40:41]
	v_cndmask_b32_e64 v23, v23, v51, s[40:41]
	v_mov_b32_dpp v29, v7 row_ror:1 row_mask:0xf bank_mask:0xf
	v_cndmask_b32_e64 v24, v24, v53, s[40:41]
	v_cndmask_b32_e64 v25, v25, v89, s[40:41]
	v_cndmask_b32_e64 v26, v26, v48, s[36:37]
	v_cndmask_b32_e64 v27, v27, v50, s[36:37]
	v_pk_mul_f32 v[22:23], v[102:103], v[22:23]
	v_cndmask_b32_e64 v28, v28, v52, s[36:37]
	v_cndmask_b32_e64 v29, v29, v88, s[36:37]
	v_pk_mul_f32 v[24:25], v[104:105], v[24:25]
	v_pk_fma_f32 v[22:23], v[98:99], v[26:27], v[22:23]
	v_pk_fma_f32 v[24:25], v[100:101], v[28:29], v[24:25]
	v_pk_fma_f32 v[22:23], v[4:5], v[94:95], v[22:23]
	v_pk_fma_f32 v[24:25], v[6:7], v[96:97], v[24:25]
	v_pk_add_f32 v[22:23], v[90:91], v[22:23]
	v_pk_add_f32 v[24:25], v[92:93], v[24:25]
	v_mul_f32_e32 v26, 0xbfb8aa3b, v22
	v_mul_f32_e32 v27, 0xbfb8aa3b, v23
	v_exp_f32_e32 v26, v26
	v_exp_f32_e32 v27, v27
	v_mul_f32_e32 v28, 0xbfb8aa3b, v24
	v_mul_f32_e32 v29, 0xbfb8aa3b, v25
	v_exp_f32_e32 v28, v28
	v_exp_f32_e32 v29, v29
	v_add_f32_e32 v26, 1.0, v26
	v_add_f32_e32 v27, 1.0, v27
	v_rcp_f32_e32 v26, v26
	v_rcp_f32_e32 v27, v27
	v_add_f32_e32 v28, 1.0, v28
	v_add_f32_e32 v29, 1.0, v29
	v_or_b32_e32 v20, 32, v64
	v_rcp_f32_e32 v28, v28
	v_rcp_f32_e32 v29, v29
	v_mad_i64_i32 v[20:21], s[4:5], v20, s89, v[32:33]
	v_lshl_add_u64 v[20:21], v[20:21], 0, v[130:131]
	global_store_dwordx4 v[20:21], v[16:19], off nt
	s_nop 0
	v_mov_b32_dpp v20, v2 row_ror:2 row_mask:0xf bank_mask:0xf
	v_pk_mul_f32 v[16:17], v[22:23], v[26:27]
	v_mov_b32_dpp v21, v3 row_ror:2 row_mask:0xf bank_mask:0xf
	v_pk_mul_f32 v[16:17], v[12:13], v[16:17]
	v_pk_mul_f32 v[12:13], v[24:25], v[28:29]
	v_mov_b32_dpp v24, v2 row_ror:1 row_mask:0xf bank_mask:0xf
	v_mov_b32_dpp v25, v3 row_ror:1 row_mask:0xf bank_mask:0xf
	v_cndmask_b32_e64 v20, v20, v45, s[40:41]
	v_cndmask_b32_e64 v21, v21, v47, s[40:41]
	v_pk_mul_f32 v[20:21], v[84:85], v[20:21]
	v_cndmask_b32_e64 v24, v24, v44, s[36:37]
	v_cndmask_b32_e64 v25, v25, v46, s[36:37]
	v_mov_b32_dpp v18, v0 row_ror:2 row_mask:0xf bank_mask:0xf
	v_mov_b32_dpp v19, v1 row_ror:2 row_mask:0xf bank_mask:0xf
	v_pk_fma_f32 v[20:21], v[76:77], v[24:25], v[20:21]
	v_mov_b32_dpp v22, v0 row_ror:1 row_mask:0xf bank_mask:0xf
	v_mov_b32_dpp v23, v1 row_ror:1 row_mask:0xf bank_mask:0xf
	v_cndmask_b32_e64 v18, v18, v41, s[40:41]
	v_cndmask_b32_e64 v19, v19, v43, s[40:41]
	v_pk_fma_f32 v[20:21], v[2:3], v[68:69], v[20:21]
	v_pk_mul_f32 v[18:19], v[82:83], v[18:19]
	v_cndmask_b32_e64 v22, v22, v40, s[36:37]
	v_cndmask_b32_e64 v23, v23, v42, s[36:37]
	v_pk_add_f32 v[20:21], v[72:73], v[20:21]
	v_pk_fma_f32 v[18:19], v[74:75], v[22:23], v[18:19]
	v_mul_f32_e32 v22, 0xbfb8aa3b, v21
	v_pk_fma_f32 v[18:19], v[0:1], v[66:67], v[18:19]
	v_exp_f32_e32 v22, v22
	v_pk_add_f32 v[18:19], v[70:71], v[18:19]
	v_pk_mul_f32 v[14:15], v[14:15], v[12:13]
	v_mul_f32_e32 v23, 0xbfb8aa3b, v18
	v_exp_f32_e32 v24, v23
	v_mul_f32_e32 v13, 0xbfb8aa3b, v19
	v_add_f32_e32 v12, 1.0, v22
	v_exp_f32_e32 v13, v13
	v_mul_f32_e32 v22, 0xbfb8aa3b, v20
	v_exp_f32_e32 v22, v22
	v_rcp_f32_e32 v23, v12
	v_add_f32_e32 v12, 1.0, v24
	v_rcp_f32_e32 v24, v12
	v_add_f32_e32 v12, 1.0, v13
	v_rcp_f32_e32 v25, v12
	v_add_f32_e32 v12, 1.0, v22
	v_rcp_f32_e32 v22, v12
	v_or_b32_e32 v12, 48, v64
	v_pk_mul_f32 v[18:19], v[18:19], v[24:25]
	s_nop 0
	v_pk_mul_f32 v[18:19], v[8:9], v[18:19]
	v_pk_mul_f32 v[8:9], v[20:21], v[22:23]
	s_nop 0
	v_pk_mul_f32 v[20:21], v[10:11], v[8:9]
	v_cvt_pk_bf16_f32 v9, v14, v15
	v_mad_i64_i32 v[14:15], s[4:5], v12, s89, v[32:33]
	v_cvt_pk_bf16_f32 v8, v16, v17
	v_cvt_pk_bf16_f32 v10, v18, v19
	v_cvt_pk_bf16_f32 v11, v20, v21
	v_lshl_add_u64 v[14:15], v[14:15], 0, v[130:131]
	global_store_dwordx4 v[14:15], v[8:11], off nt
	s_and_saveexec_b64 s[4:5], s[44:45]
	s_cbranch_execz .LBB0_118
	v_lshl_add_u64 v[8:9], s[0:1], 0, v[204:205]
	v_mov_b64_e32 v[10:11], s[62:63]
	v_mad_u64_u32 v[10:11], s[0:1], v8, s90, v[10:11]
	v_mad_i32_i24 v11, v9, s90, v11
	v_lshl_add_u64 v[8:9], v[210:211], 2, v[10:11]
	v_cmp_gt_i32_e32 vcc, s81, v12
	global_store_dwordx4 v[8:9], v[4:7], off nt
	global_store_dwordx4 v[8:9], v[0:3], off offset:16 nt
	v_cndmask_b32_e32 v8, 63, v229, vcc
	v_mov_b32_e32 v9, 0xffe
	v_and_b32_e32 v8, v8, v12
	v_cndmask_b32_e32 v9, 62, v9, vcc
	v_cmp_ge_u32_e64 s[0:1], v8, v9
	s_and_b64 exec, exec, s[0:1]
	s_cbranch_execz .LBB0_118
	s_addk_i32 s7, 0x8000
	s_lshr_b32 s0, s7, 6
	s_ashr_i32 s1, s6, 6
	v_mov_b32_e32 v10, s0
	v_mov_b32_e32 v11, s1
	v_cndmask_b32_e32 v12, v10, v11, vcc
	v_mov_b32_e32 v10, 0x19120000
	v_mov_b32_e32 v11, 0x19070000
	v_cndmask_b32_e32 v64, v10, v11, vcc
	v_add_u32_e32 v12, s70, v12
	v_sub_u32_e32 v8, v8, v9
	v_lshl_add_u64 v[10:11], s[64:65], 0, v[64:65]
	v_lshl_add_u32 v8, v12, 1, v8
	v_mad_i64_i32 v[8:9], s[0:1], v8, s90, v[10:11]
	v_lshl_add_u64 v[8:9], v[210:211], 2, v[8:9]
	global_store_dwordx4 v[8:9], v[4:7], off nt
	global_store_dwordx4 v[8:9], v[0:3], off offset:16 nt
